# norm fusion v2: per-row scales computed once per in-proj phase (a workgroup's tiles share one row block), per tile only the 128 multiplies
# speedup vs baseline: 1.0148x; 1.0127x over previous
.LBB0_182:
	s_or_b64 exec, exec, s[38:39]
	v_readlane_b32 s88, v255, 32
	s_and_b32 s88, s88, 0x20ec4000
	s_mov_b32 s89, 0
	v_readlane_b32 s2, v255, 30
	v_readlane_b32 s3, v255, 31
	s_waitcnt lgkmcnt(0)
	v_mov_b32_e32 v0, v177
	s_barrier
	s_mov_b32 s3, s35
	v_writelane_b32 v255, s2, 30
	v_mbcnt_lo_u32_b32 v0, -1, v0
	v_mbcnt_hi_u32_b32 v0, -1, v0
	v_writelane_b32 v255, s3, 31
	v_readlane_b32 s2, v254, 17
	v_add_u32_e32 v5, s85, v0
	v_readlane_b32 s3, v254, 18
	s_andn2_b64 vcc, exec, s[2:3]
	v_readfirstlane_b32 s34, v5
	s_cbranch_vccnz .LBB0_194
	v_lshlrev_b32_e32 v4, 4, v5
	v_add_u32_e32 v2, 0x2000, v4
	v_ashrrev_i32_e32 v1, 31, v2
	v_lshrrev_b32_e32 v1, 22, v1
	v_add_u32_e32 v1, v2, v1
	v_ashrrev_i32_e32 v1, 10, v1
	v_mul_i32_i24_e32 v3, 0x400, v1
	v_sub_u32_e32 v2, v2, v3
	v_lshrrev_b32_e32 v3, 4, v2
	v_bitop3_b32 v3, v3, v2, 32 bitop3:0x6c
	v_ashrrev_i32_e32 v2, 31, v3
	v_lshrrev_b32_e32 v2, 26, v2
	v_add_u32_e32 v6, v3, v2
	v_lshlrev_b32_e32 v7, 3, v1
	v_readlane_b32 s2, v255, 30
	v_ashrrev_i32_e32 v2, 6, v6
	v_and_b32_e32 v7, -16, v7
	v_readlane_b32 s3, v255, 31
	v_add_u32_e32 v7, v2, v7
	v_and_b32_e32 v8, 3, v2
	s_mov_b32 s3, 0xfffe0
	v_lshrrev_b32_e32 v9, 2, v7
	v_lshlrev_b32_e32 v10, 1, v7
	v_and_b32_e32 v6, 0xc0, v6
	v_and_or_b32 v8, v7, s3, v8
	v_and_b32_e32 v9, 4, v9
	v_and_b32_e32 v10, 24, v10
	v_sub_u32_e32 v3, v3, v6
	v_mov_b32_e32 v12, 1
	v_or3_b32 v8, v8, v9, v10
	v_lshlrev_b32_e32 v9, 5, v1
	v_ashrrev_i16_sdwa v3, v12, sext(v3) dst_sel:DWORD dst_unused:UNUSED_PAD src0_sel:DWORD src1_sel:BYTE_0
	v_and_b32_e32 v9, 32, v9
	v_bfe_i32 v3, v3, 0, 16
	v_add_lshl_u32 v6, v9, v3, 1
	v_lshl_add_u32 v128, v8, 12, v6
	v_lshl_add_u32 v130, v7, 12, v6
	v_bfe_i32 v6, v5, 27, 1
	v_lshrrev_b32_e32 v6, 22, v6
	v_add_u32_e32 v6, v4, v6
	v_and_b32_e32 v6, 0xfffffc00, v6
	v_sub_u32_e32 v4, v4, v6
	v_lshrrev_b32_e32 v6, 4, v4
	v_ashrrev_i32_e32 v8, 31, v5
	v_bitop3_b32 v6, v6, v4, 32 bitop3:0x6c
	v_lshrrev_b32_e32 v8, 26, v8
	v_ashrrev_i32_e32 v4, 31, v6
	v_add_u32_e32 v5, v5, v8
	v_lshrrev_b32_e32 v4, 26, v4
	v_ashrrev_i32_e32 v5, 6, v5
	v_add_u32_e32 v7, v6, v4
	v_lshlrev_b32_e32 v8, 3, v5
	v_ashrrev_i32_e32 v4, 6, v7
	v_and_b32_e32 v8, -16, v8
	s_mul_hi_u32 s1, s2, 0x1b00000
	s_mul_i32 s2, s2, 0x1b00000
	v_readlane_b32 s12, v253, 2
	v_add_u32_e32 v8, v4, v8
	v_readlane_b32 s13, v253, 3
	s_add_u32 s49, s12, s2
	v_and_b32_e32 v9, 3, v4
	v_lshrrev_b32_e32 v10, 2, v8
	v_lshlrev_b32_e32 v11, 1, v8
	v_and_b32_e32 v7, 0xc0, v7
	s_addc_u32 s52, s13, s1
	s_ashr_i32 s2, s34, 6
	v_and_or_b32 v9, v8, s3, v9
	v_and_b32_e32 v10, 4, v10
	v_and_b32_e32 v11, 24, v11
	v_sub_u32_e32 v6, v6, v7
	s_ashr_i32 s1, s34, 8
	s_lshl_b32 s53, s2, 10
	v_or3_b32 v9, v9, v10, v11
	v_lshlrev_b32_e32 v10, 5, v5
	v_ashrrev_i16_sdwa v6, v12, sext(v6) dst_sel:DWORD dst_unused:UNUSED_PAD src0_sel:DWORD src1_sel:BYTE_0
	v_readlane_b32 s12, v254, 36
	v_and_b32_e32 v10, 32, v10
	v_bfe_i32 v6, v6, 0, 16
	v_readlane_b32 s13, v254, 37
	s_add_u32 s70, s49, s12
	v_add_lshl_u32 v7, v10, v6, 1
	s_addc_u32 s71, s52, s13
	s_add_i32 s60, s53, 0
	v_lshl_add_u32 v176, v9, 12, v7
	s_add_i32 m0, s60, 0x10000
	v_readlane_b32 s12, v254, 40
	global_load_lds_dwordx4 v176, s[70:71]
	s_add_i32 m0, s60, 0x12000
	v_lshl_add_u32 v132, v8, 12, v7
	global_load_lds_dwordx4 v128, s[70:71]
	s_mov_b32 m0, s60
	v_readlane_b32 s13, v254, 41
	s_add_u32 s12, s12, s88
	s_addc_u32 s13, s13, 0
	s_add_i32 s61, s60, 0x2000
	s_nop 3
	global_load_lds_dwordx4 v132, s[12:13]
	s_mov_b32 m0, s61
	s_nop 0
	global_load_lds_dwordx4 v130, s[12:13]
	s_add_u32 s12, s70, 0x80000
	s_addc_u32 s13, s71, 0
	s_add_i32 m0, s60, 0x14000
	s_add_i32 s74, s60, 0x4000
	global_load_lds_dwordx4 v176, s[12:13]
	s_add_i32 m0, s60, 0x16000
	s_add_i32 s75, s60, 0x6000
	global_load_lds_dwordx4 v128, s[12:13]
	v_readlane_b32 s12, v254, 42
	s_mov_b32 m0, s74
	v_readlane_b32 s13, v254, 43
	s_add_u32 s12, s12, s88
	s_addc_u32 s13, s13, 0
	s_cmp_lg_u32 s1, 1
	s_nop 3
	global_load_lds_dwordx4 v132, s[12:13]
	s_mov_b32 m0, s75
	s_nop 0
	global_load_lds_dwordx4 v130, s[12:13]
	s_cbranch_scc1 .LBB0_185
	s_barrier

.LBB0_189:
	s_add_u32 s1, s68, 0xfff80080
	s_addc_u32 s2, s69, -1
	s_add_i32 s3, 0, 0x10000
	v_add_u32_e32 v154, s3, v143
	ds_read_b128 v[138:141], v154
	ds_read_b128 v[146:149], v154 offset:1024
	ds_read_b128 v[150:153], v154 offset:2048
	ds_read_b128 v[154:157], v154 offset:3072
	s_cmp_eq_u32 s87, 28
	s_cselect_b32 s73, s43, s2
	s_cselect_b32 s72, s81, s1
	s_cselect_b32 s71, s41, s86
	s_cselect_b32 s70, s82, s83
	v_lshl_add_u64 v[174:175], s[68:69], 0, v[134:135]
	s_add_i32 m0, s60, 0xc000
	ds_read_b128 v[158:161], v145
	ds_read_b128 v[162:165], v145 offset:1024
	ds_read_b128 v[166:169], v145 offset:2048
	ds_read_b128 v[170:173], v145 offset:3072
	ds_read_b128 v[182:185], v145 offset:4096
	ds_read_b128 v[206:209], v145 offset:5120
	ds_read_b128 v[210:213], v145 offset:6144
	ds_read_b128 v[214:217], v145 offset:7168
	global_load_lds_dwordx4 v[174:175], off
	v_lshl_add_u64 v[174:175], s[68:69], 0, v[136:137]
	s_add_i32 m0, s60, 0xe000
	s_nop 0
	global_load_lds_dwordx4 v[174:175], off
	s_waitcnt lgkmcnt(8)
	s_barrier
	s_waitcnt lgkmcnt(0)
	s_setprio 1
	s_waitcnt lgkmcnt(0)
	v_mfma_f32_16x16x32_bf16 v[124:127], v[138:141], v[158:161], v[124:127]
	v_mfma_f32_16x16x32_bf16 v[120:123], v[150:153], v[158:161], v[120:123]
	v_mfma_f32_16x16x32_bf16 v[116:119], v[138:141], v[166:169], v[116:119]
	v_mfma_f32_16x16x32_bf16 v[108:111], v[150:153], v[166:169], v[108:111]
	v_mfma_f32_16x16x32_bf16 v[100:103], v[138:141], v[182:185], v[100:103]
	v_mfma_f32_16x16x32_bf16 v[92:95], v[150:153], v[182:185], v[92:95]
	v_mfma_f32_16x16x32_bf16 v[84:87], v[138:141], v[210:213], v[84:87]
	v_mfma_f32_16x16x32_bf16 v[76:79], v[150:153], v[210:213], v[76:79]
	v_mfma_f32_16x16x32_bf16 v[124:127], v[146:149], v[162:165], v[124:127]
	v_mfma_f32_16x16x32_bf16 v[120:123], v[154:157], v[162:165], v[120:123]
	v_mfma_f32_16x16x32_bf16 v[116:119], v[146:149], v[170:173], v[116:119]
	v_mfma_f32_16x16x32_bf16 v[108:111], v[154:157], v[170:173], v[108:111]
	v_mfma_f32_16x16x32_bf16 v[100:103], v[146:149], v[206:209], v[100:103]
	v_mfma_f32_16x16x32_bf16 v[92:95], v[154:157], v[206:209], v[92:95]
	v_mfma_f32_16x16x32_bf16 v[84:87], v[146:149], v[214:217], v[84:87]
	v_mfma_f32_16x16x32_bf16 v[76:79], v[154:157], v[214:217], v[76:79]
	s_setprio 0
	s_barrier
	s_add_i32 s1, 0, 0x14000
	v_add_u32_e32 v174, s1, v143
	s_add_i32 s2, s3, s53
	ds_read_b128 v[218:221], v174
	ds_read_b128 v[222:225], v174 offset:1024
	ds_read_b128 v[226:229], v174 offset:2048
	ds_read_b128 v[230:233], v174 offset:3072
	v_lshl_add_u64 v[174:175], s[70:71], 0, v[176:177]
	s_mov_b32 m0, s2
	v_lshl_add_u64 v[186:187], s[70:71], 0, v[128:129]
	global_load_lds_dwordx4 v[174:175], off
	s_add_i32 m0, s2, 0x2000
	s_nop 0
	global_load_lds_dwordx4 v[186:187], off
	s_barrier
	s_waitcnt lgkmcnt(0)
	s_setprio 1
	s_waitcnt lgkmcnt(0)
	v_mfma_f32_16x16x32_bf16 v[112:115], v[218:221], v[158:161], v[112:115]
	v_mfma_f32_16x16x32_bf16 v[104:107], v[226:229], v[158:161], v[104:107]
	v_mfma_f32_16x16x32_bf16 v[96:99], v[218:221], v[166:169], v[96:99]
	v_mfma_f32_16x16x32_bf16 v[88:91], v[226:229], v[166:169], v[88:91]
	v_mfma_f32_16x16x32_bf16 v[80:83], v[218:221], v[182:185], v[80:83]
	v_mfma_f32_16x16x32_bf16 v[72:75], v[226:229], v[182:185], v[72:75]
	v_mfma_f32_16x16x32_bf16 v[68:71], v[218:221], v[210:213], v[68:71]
	v_mfma_f32_16x16x32_bf16 v[64:67], v[226:229], v[210:213], v[64:67]
	v_mfma_f32_16x16x32_bf16 v[112:115], v[222:225], v[162:165], v[112:115]
	v_mfma_f32_16x16x32_bf16 v[104:107], v[230:233], v[162:165], v[104:107]
	v_mfma_f32_16x16x32_bf16 v[96:99], v[222:225], v[170:173], v[96:99]
	v_mfma_f32_16x16x32_bf16 v[88:91], v[230:233], v[170:173], v[88:91]
	v_mfma_f32_16x16x32_bf16 v[80:83], v[222:225], v[206:209], v[80:83]
	v_mfma_f32_16x16x32_bf16 v[72:75], v[230:233], v[206:209], v[72:75]
	v_mfma_f32_16x16x32_bf16 v[68:71], v[222:225], v[214:217], v[68:71]
	v_mfma_f32_16x16x32_bf16 v[64:67], v[230:233], v[214:217], v[64:67]
	s_setprio 0
	s_mov_b32 m0, s60
	v_lshl_add_u64 v[200:201], s[72:73], 0, v[132:133]
	s_barrier
	ds_read_b128 v[158:161], v145 offset:16384
	ds_read_b128 v[162:165], v145 offset:17408
	ds_read_b128 v[166:169], v145 offset:18432
	ds_read_b128 v[170:173], v145 offset:19456
	ds_read_b128 v[182:185], v145 offset:20480
	ds_read_b128 v[206:209], v145 offset:21504
	ds_read_b128 v[210:213], v145 offset:22528
	ds_read_b128 v[214:217], v145 offset:23552
	global_load_lds_dwordx4 v[200:201], off
	v_lshl_add_u64 v[202:203], s[72:73], 0, v[130:131]
	s_mov_b32 m0, s61
	s_nop 0
	global_load_lds_dwordx4 v[202:203], off
	s_barrier
	s_waitcnt lgkmcnt(0)
	s_setprio 1
	s_waitcnt lgkmcnt(0)
	v_mfma_f32_16x16x32_bf16 v[60:63], v[138:141], v[158:161], v[60:63]
	v_mfma_f32_16x16x32_bf16 v[56:59], v[150:153], v[158:161], v[56:59]
	v_mfma_f32_16x16x32_bf16 v[52:55], v[138:141], v[166:169], v[52:55]
	v_mfma_f32_16x16x32_bf16 v[44:47], v[150:153], v[166:169], v[44:47]
	v_mfma_f32_16x16x32_bf16 v[36:39], v[138:141], v[182:185], v[36:39]
	v_mfma_f32_16x16x32_bf16 v[28:31], v[150:153], v[182:185], v[28:31]
	v_mfma_f32_16x16x32_bf16 v[20:23], v[138:141], v[210:213], v[20:23]
	v_mfma_f32_16x16x32_bf16 v[12:15], v[150:153], v[210:213], v[12:15]
	v_mfma_f32_16x16x32_bf16 v[60:63], v[146:149], v[162:165], v[60:63]
	v_mfma_f32_16x16x32_bf16 v[56:59], v[154:157], v[162:165], v[56:59]
	v_mfma_f32_16x16x32_bf16 v[52:55], v[146:149], v[170:173], v[52:55]
	v_mfma_f32_16x16x32_bf16 v[44:47], v[154:157], v[170:173], v[44:47]
	v_mfma_f32_16x16x32_bf16 v[36:39], v[146:149], v[206:209], v[36:39]
	v_mfma_f32_16x16x32_bf16 v[28:31], v[154:157], v[206:209], v[28:31]
	v_mfma_f32_16x16x32_bf16 v[20:23], v[146:149], v[214:217], v[20:23]
	v_mfma_f32_16x16x32_bf16 v[12:15], v[154:157], v[214:217], v[12:15]
	s_setprio 0
	s_barrier
	s_add_u32 s2, s70, 0x80000
	s_addc_u32 s3, s71, 0
	s_add_i32 s1, s1, s53
	v_lshl_add_u64 v[138:139], s[2:3], 0, v[176:177]
	s_mov_b32 m0, s1
	s_nop 0
	global_load_lds_dwordx4 v[138:139], off
	v_lshl_add_u64 v[138:139], s[2:3], 0, v[128:129]
	s_add_i32 m0, s1, 0x2000
	s_nop 0
	global_load_lds_dwordx4 v[138:139], off
	s_waitcnt vmcnt(6)
	s_barrier
	s_setprio 1
	v_mfma_f32_16x16x32_bf16 v[48:51], v[218:221], v[158:161], v[48:51]
	v_mfma_f32_16x16x32_bf16 v[40:43], v[226:229], v[158:161], v[40:43]
	v_mfma_f32_16x16x32_bf16 v[32:35], v[218:221], v[166:169], v[32:35]
	v_mfma_f32_16x16x32_bf16 v[24:27], v[226:229], v[166:169], v[24:27]
	v_mfma_f32_16x16x32_bf16 v[16:19], v[218:221], v[182:185], v[16:19]
	v_mfma_f32_16x16x32_bf16 v[8:11], v[226:229], v[182:185], v[8:11]
	v_mfma_f32_16x16x32_bf16 v[4:7], v[218:221], v[210:213], v[4:7]
	v_mfma_f32_16x16x32_bf16 v[0:3], v[226:229], v[210:213], v[0:3]
	v_mfma_f32_16x16x32_bf16 v[48:51], v[222:225], v[162:165], v[48:51]
	v_mfma_f32_16x16x32_bf16 v[40:43], v[230:233], v[162:165], v[40:43]
	v_mfma_f32_16x16x32_bf16 v[32:35], v[222:225], v[170:173], v[32:35]
	v_mfma_f32_16x16x32_bf16 v[24:27], v[230:233], v[170:173], v[24:27]
	v_mfma_f32_16x16x32_bf16 v[16:19], v[222:225], v[206:209], v[16:19]
	v_mfma_f32_16x16x32_bf16 v[8:11], v[230:233], v[206:209], v[8:11]
	v_mfma_f32_16x16x32_bf16 v[4:7], v[222:225], v[214:217], v[4:7]
	v_mfma_f32_16x16x32_bf16 v[0:3], v[230:233], v[214:217], v[0:3]
	s_setprio 0
	s_add_i32 s1, 0, 0x18000
	v_add_u32_e32 v154, s1, v143
	s_barrier
	ds_read_b128 v[138:141], v154
	ds_read_b128 v[146:149], v154 offset:1024
	ds_read_b128 v[150:153], v154 offset:2048
	ds_read_b128 v[154:157], v154 offset:3072
	s_add_u32 s2, s72, 0x80000
	s_addc_u32 s3, s73, 0
	s_mov_b32 m0, s74
	v_lshl_add_u64 v[204:205], s[2:3], 0, v[132:133]
	ds_read_b128 v[158:161], v145 offset:32768
	ds_read_b128 v[162:165], v145 offset:33792
	ds_read_b128 v[166:169], v145 offset:34816
	ds_read_b128 v[170:173], v145 offset:35840
	ds_read_b128 v[182:185], v145 offset:36864
	ds_read_b128 v[206:209], v145 offset:37888
	ds_read_b128 v[210:213], v145 offset:38912
	ds_read_b128 v[214:217], v145 offset:39936
	global_load_lds_dwordx4 v[204:205], off
	v_lshl_add_u64 v[204:205], s[2:3], 0, v[130:131]
	s_mov_b32 m0, s75
	s_nop 0
	global_load_lds_dwordx4 v[204:205], off
	s_waitcnt lgkmcnt(8)
	s_barrier
	s_waitcnt lgkmcnt(0)
	s_setprio 1
	s_waitcnt lgkmcnt(0)
	v_mfma_f32_16x16x32_bf16 v[124:127], v[138:141], v[158:161], v[124:127]
	v_mfma_f32_16x16x32_bf16 v[120:123], v[150:153], v[158:161], v[120:123]
	v_mfma_f32_16x16x32_bf16 v[116:119], v[138:141], v[166:169], v[116:119]
	v_mfma_f32_16x16x32_bf16 v[108:111], v[150:153], v[166:169], v[108:111]
	v_mfma_f32_16x16x32_bf16 v[100:103], v[138:141], v[182:185], v[100:103]
	v_mfma_f32_16x16x32_bf16 v[92:95], v[150:153], v[182:185], v[92:95]
	v_mfma_f32_16x16x32_bf16 v[84:87], v[138:141], v[210:213], v[84:87]
	v_mfma_f32_16x16x32_bf16 v[76:79], v[150:153], v[210:213], v[76:79]
	v_mfma_f32_16x16x32_bf16 v[124:127], v[146:149], v[162:165], v[124:127]
	v_mfma_f32_16x16x32_bf16 v[120:123], v[154:157], v[162:165], v[120:123]
	v_mfma_f32_16x16x32_bf16 v[116:119], v[146:149], v[170:173], v[116:119]
	v_mfma_f32_16x16x32_bf16 v[108:111], v[154:157], v[170:173], v[108:111]
	v_mfma_f32_16x16x32_bf16 v[100:103], v[146:149], v[206:209], v[100:103]
	v_mfma_f32_16x16x32_bf16 v[92:95], v[154:157], v[206:209], v[92:95]
	v_mfma_f32_16x16x32_bf16 v[84:87], v[146:149], v[214:217], v[84:87]
	v_mfma_f32_16x16x32_bf16 v[76:79], v[154:157], v[214:217], v[76:79]
	s_setprio 0
	s_barrier
	s_add_i32 s12, 0, 0x1c000
	s_add_i32 s1, s1, s53
	v_add_u32_e32 v188, s12, v143
	v_lshl_add_u64 v[174:175], v[174:175], 0, s[20:21]
	s_mov_b32 m0, s1
	ds_read_b128 v[218:221], v188
	ds_read_b128 v[222:225], v188 offset:1024
	ds_read_b128 v[226:229], v188 offset:2048
	ds_read_b128 v[230:233], v188 offset:3072
	global_load_lds_dwordx4 v[174:175], off
	v_lshl_add_u64 v[174:175], v[186:187], 0, s[20:21]
	s_add_i32 m0, s1, 0x2000
	s_nop 0
	global_load_lds_dwordx4 v[174:175], off
	s_barrier
	s_waitcnt lgkmcnt(0)
	s_setprio 1
	s_waitcnt lgkmcnt(0)
	v_mfma_f32_16x16x32_bf16 v[112:115], v[218:221], v[158:161], v[112:115]
	v_mfma_f32_16x16x32_bf16 v[104:107], v[226:229], v[158:161], v[104:107]
	v_mfma_f32_16x16x32_bf16 v[96:99], v[218:221], v[166:169], v[96:99]
	v_mfma_f32_16x16x32_bf16 v[88:91], v[226:229], v[166:169], v[88:91]
	v_mfma_f32_16x16x32_bf16 v[80:83], v[218:221], v[182:185], v[80:83]
	v_mfma_f32_16x16x32_bf16 v[72:75], v[226:229], v[182:185], v[72:75]
	v_mfma_f32_16x16x32_bf16 v[68:71], v[218:221], v[210:213], v[68:71]
	v_mfma_f32_16x16x32_bf16 v[64:67], v[226:229], v[210:213], v[64:67]
	v_mfma_f32_16x16x32_bf16 v[112:115], v[222:225], v[162:165], v[112:115]
	v_mfma_f32_16x16x32_bf16 v[104:107], v[230:233], v[162:165], v[104:107]
	v_mfma_f32_16x16x32_bf16 v[96:99], v[222:225], v[170:173], v[96:99]
	v_mfma_f32_16x16x32_bf16 v[88:91], v[230:233], v[170:173], v[88:91]
	v_mfma_f32_16x16x32_bf16 v[80:83], v[222:225], v[206:209], v[80:83]
	v_mfma_f32_16x16x32_bf16 v[72:75], v[230:233], v[206:209], v[72:75]
	v_mfma_f32_16x16x32_bf16 v[68:71], v[222:225], v[214:217], v[68:71]
	v_mfma_f32_16x16x32_bf16 v[64:67], v[230:233], v[214:217], v[64:67]
	s_setprio 0
	s_mov_b32 m0, s76
	v_lshl_add_u64 v[174:175], v[200:201], 0, s[20:21]
	s_barrier
	ds_read_b128 v[158:161], v145 offset:49152
	ds_read_b128 v[162:165], v145 offset:50176
	ds_read_b128 v[166:169], v145 offset:51200
	ds_read_b128 v[170:173], v145 offset:52224
	ds_read_b128 v[182:185], v145 offset:53248
	ds_read_b128 v[206:209], v145 offset:54272
	ds_read_b128 v[210:213], v145 offset:55296
	ds_read_b128 v[214:217], v145 offset:56320
	global_load_lds_dwordx4 v[174:175], off
	v_lshl_add_u64 v[174:175], v[202:203], 0, s[20:21]
	s_mov_b32 m0, s77
	s_nop 0
	global_load_lds_dwordx4 v[174:175], off
	s_barrier
	s_waitcnt lgkmcnt(0)
	s_setprio 1
	s_waitcnt lgkmcnt(0)
	v_mfma_f32_16x16x32_bf16 v[60:63], v[138:141], v[158:161], v[60:63]
	v_mfma_f32_16x16x32_bf16 v[56:59], v[150:153], v[158:161], v[56:59]
	v_mfma_f32_16x16x32_bf16 v[52:55], v[138:141], v[166:169], v[52:55]
	v_mfma_f32_16x16x32_bf16 v[44:47], v[150:153], v[166:169], v[44:47]
	v_mfma_f32_16x16x32_bf16 v[36:39], v[138:141], v[182:185], v[36:39]
	v_mfma_f32_16x16x32_bf16 v[28:31], v[150:153], v[182:185], v[28:31]
	v_mfma_f32_16x16x32_bf16 v[20:23], v[138:141], v[210:213], v[20:23]
	v_mfma_f32_16x16x32_bf16 v[12:15], v[150:153], v[210:213], v[12:15]
	v_mfma_f32_16x16x32_bf16 v[60:63], v[146:149], v[162:165], v[60:63]
	v_mfma_f32_16x16x32_bf16 v[56:59], v[154:157], v[162:165], v[56:59]
	v_mfma_f32_16x16x32_bf16 v[52:55], v[146:149], v[170:173], v[52:55]
	v_mfma_f32_16x16x32_bf16 v[44:47], v[154:157], v[170:173], v[44:47]
	v_mfma_f32_16x16x32_bf16 v[36:39], v[146:149], v[206:209], v[36:39]
	v_mfma_f32_16x16x32_bf16 v[28:31], v[154:157], v[206:209], v[28:31]
	v_mfma_f32_16x16x32_bf16 v[20:23], v[146:149], v[214:217], v[20:23]
	v_mfma_f32_16x16x32_bf16 v[12:15], v[154:157], v[214:217], v[12:15]
	s_setprio 0
	s_barrier
	s_add_u32 s2, s70, 0x80080
	s_addc_u32 s3, s71, 0
	s_add_i32 s1, s12, s53
	v_lshl_add_u64 v[138:139], s[2:3], 0, v[176:177]
	s_mov_b32 m0, s1
	s_nop 0
	global_load_lds_dwordx4 v[138:139], off
	v_lshl_add_u64 v[138:139], s[2:3], 0, v[128:129]
	s_add_i32 m0, s1, 0x2000
	s_nop 0
	global_load_lds_dwordx4 v[138:139], off
	s_waitcnt vmcnt(6)
	s_barrier
	s_setprio 1
	v_mfma_f32_16x16x32_bf16 v[48:51], v[218:221], v[158:161], v[48:51]
	v_mfma_f32_16x16x32_bf16 v[40:43], v[226:229], v[158:161], v[40:43]
	v_mfma_f32_16x16x32_bf16 v[32:35], v[218:221], v[166:169], v[32:35]
	v_mfma_f32_16x16x32_bf16 v[24:27], v[226:229], v[166:169], v[24:27]
	v_mfma_f32_16x16x32_bf16 v[16:19], v[218:221], v[182:185], v[16:19]
	v_mfma_f32_16x16x32_bf16 v[8:11], v[226:229], v[182:185], v[8:11]
	v_mfma_f32_16x16x32_bf16 v[4:7], v[218:221], v[210:213], v[4:7]
	v_mfma_f32_16x16x32_bf16 v[0:3], v[226:229], v[210:213], v[0:3]
	v_mfma_f32_16x16x32_bf16 v[48:51], v[222:225], v[162:165], v[48:51]
	v_mfma_f32_16x16x32_bf16 v[40:43], v[230:233], v[162:165], v[40:43]
	v_mfma_f32_16x16x32_bf16 v[32:35], v[222:225], v[170:173], v[32:35]
	v_mfma_f32_16x16x32_bf16 v[24:27], v[230:233], v[170:173], v[24:27]
	v_mfma_f32_16x16x32_bf16 v[16:19], v[222:225], v[206:209], v[16:19]
	v_mfma_f32_16x16x32_bf16 v[8:11], v[230:233], v[206:209], v[8:11]
	v_mfma_f32_16x16x32_bf16 v[4:7], v[222:225], v[214:217], v[4:7]
	v_mfma_f32_16x16x32_bf16 v[0:3], v[230:233], v[214:217], v[0:3]
	s_setprio 0
	s_add_i32 s87, s87, 2
	s_add_u32 s68, s68, 0x100
	s_addc_u32 s69, s69, 0
	s_add_u32 s83, s83, 0x100
	s_addc_u32 s86, s86, 0
	s_cmp_gt_u32 s87, 29
	s_barrier
	s_cbranch_scc0 .LBB0_189
	s_cmp_eq_u32 s88, 0
	s_cbranch_scc1 .Lrs_skip
	s_cmp_lg_u32 s89, 0
	s_cbranch_scc1 .Lrs_mul
	v_readlane_b32 s98, v255, 1
	v_readlane_b32 s99, v255, 2
	v_lshl_add_u32 v200, s80, 8, v142
	v_bfe_u32 v201, v144, 3, 2
	v_lshlrev_b32_e32 v201, 5, v201
	v_lshl_add_u32 v200, v200, 7, v201
	v_add_u32_e32 v201, 0x1000, v200
	v_add_u32_e32 v202, 0x4000, v200
	v_add_u32_e32 v203, 0x5000, v200
	v_mbcnt_lo_u32_b32 v204, -1, 0
	v_mbcnt_hi_u32_b32 v204, -1, v204
	v_xor_b32_e32 v205, 16, v204
	v_xor_b32_e32 v204, 32, v204
	v_lshlrev_b32_e32 v205, 2, v205
	v_lshlrev_b32_e32 v204, 2, v204
	global_load_dwordx4 v[208:211], v200, s[98:99]
	global_load_dwordx4 v[212:215], v200, s[98:99] offset:16
	global_load_dwordx4 v[216:219], v200, s[98:99] offset:2048
	global_load_dwordx4 v[220:223], v200, s[98:99] offset:2064
	global_load_dwordx4 v[224:227], v201, s[98:99]
	global_load_dwordx4 v[228:231], v201, s[98:99] offset:16
	global_load_dwordx4 v[232:235], v201, s[98:99] offset:2048
	global_load_dwordx4 v[236:239], v201, s[98:99] offset:2064
	s_waitcnt vmcnt(0)
	v_add_f32_e32 v208, v208, v209
	v_add_f32_e32 v210, v210, v211
	v_add_f32_e32 v212, v212, v213
	v_add_f32_e32 v214, v214, v215
	v_add_f32_e32 v208, v208, v210
	v_add_f32_e32 v212, v212, v214
	v_add_f32_e32 v190, v208, v212
	v_add_f32_e32 v216, v216, v217
	v_add_f32_e32 v218, v218, v219
	v_add_f32_e32 v220, v220, v221
	v_add_f32_e32 v222, v222, v223
	v_add_f32_e32 v216, v216, v218
	v_add_f32_e32 v220, v220, v222
	v_add_f32_e32 v191, v216, v220
	v_add_f32_e32 v224, v224, v225
	v_add_f32_e32 v226, v226, v227
	v_add_f32_e32 v228, v228, v229
	v_add_f32_e32 v230, v230, v231
	v_add_f32_e32 v224, v224, v226
	v_add_f32_e32 v228, v228, v230
	v_add_f32_e32 v192, v224, v228
	v_add_f32_e32 v232, v232, v233
	v_add_f32_e32 v234, v234, v235
	v_add_f32_e32 v236, v236, v237
	v_add_f32_e32 v238, v238, v239
	v_add_f32_e32 v232, v232, v234
	v_add_f32_e32 v236, v236, v238
	v_add_f32_e32 v194, v232, v236
	global_load_dwordx4 v[208:211], v202, s[98:99]
	global_load_dwordx4 v[212:215], v202, s[98:99] offset:16
	global_load_dwordx4 v[216:219], v202, s[98:99] offset:2048
	global_load_dwordx4 v[220:223], v202, s[98:99] offset:2064
	global_load_dwordx4 v[224:227], v203, s[98:99]
	global_load_dwordx4 v[228:231], v203, s[98:99] offset:16
	global_load_dwordx4 v[232:235], v203, s[98:99] offset:2048
	global_load_dwordx4 v[236:239], v203, s[98:99] offset:2064
	s_waitcnt vmcnt(0)
	v_add_f32_e32 v208, v208, v209
	v_add_f32_e32 v210, v210, v211
	v_add_f32_e32 v212, v212, v213
	v_add_f32_e32 v214, v214, v215
	v_add_f32_e32 v208, v208, v210
	v_add_f32_e32 v212, v212, v214
	v_add_f32_e32 v195, v208, v212
	v_add_f32_e32 v216, v216, v217
	v_add_f32_e32 v218, v218, v219
	v_add_f32_e32 v220, v220, v221
	v_add_f32_e32 v222, v222, v223
	v_add_f32_e32 v216, v216, v218
	v_add_f32_e32 v220, v220, v222
	v_add_f32_e32 v196, v216, v220
	v_add_f32_e32 v224, v224, v225
	v_add_f32_e32 v226, v226, v227
	v_add_f32_e32 v228, v228, v229
	v_add_f32_e32 v230, v230, v231
	v_add_f32_e32 v224, v224, v226
	v_add_f32_e32 v228, v228, v230
	v_add_f32_e32 v198, v224, v228
	v_add_f32_e32 v232, v232, v233
	v_add_f32_e32 v234, v234, v235
	v_add_f32_e32 v236, v236, v237
	v_add_f32_e32 v238, v238, v239
	v_add_f32_e32 v232, v232, v234
	v_add_f32_e32 v236, v236, v238
	v_add_f32_e32 v248, v232, v236
	ds_bpermute_b32 v240, v205, v190
	ds_bpermute_b32 v241, v205, v191
	ds_bpermute_b32 v242, v205, v192
	ds_bpermute_b32 v243, v205, v194
	ds_bpermute_b32 v244, v205, v195
	ds_bpermute_b32 v245, v205, v196
	ds_bpermute_b32 v246, v205, v198
	ds_bpermute_b32 v247, v205, v248
	s_waitcnt lgkmcnt(0)
	v_add_f32_e32 v190, v190, v240
	v_add_f32_e32 v191, v191, v241
	v_add_f32_e32 v192, v192, v242
	v_add_f32_e32 v194, v194, v243
	v_add_f32_e32 v195, v195, v244
	v_add_f32_e32 v196, v196, v245
	v_add_f32_e32 v198, v198, v246
	v_add_f32_e32 v248, v248, v247
	ds_bpermute_b32 v240, v204, v190
	ds_bpermute_b32 v241, v204, v191
	ds_bpermute_b32 v242, v204, v192
	ds_bpermute_b32 v243, v204, v194
	ds_bpermute_b32 v244, v204, v195
	ds_bpermute_b32 v245, v204, v196
	ds_bpermute_b32 v246, v204, v198
	ds_bpermute_b32 v247, v204, v248
	s_waitcnt lgkmcnt(0)
	v_add_f32_e32 v190, v190, v240
	v_add_f32_e32 v191, v191, v241
	v_add_f32_e32 v192, v192, v242
	v_add_f32_e32 v194, v194, v243
	v_add_f32_e32 v195, v195, v244
	v_add_f32_e32 v196, v196, v245
	v_add_f32_e32 v198, v198, v246
	v_add_f32_e32 v248, v248, v247
	v_mul_f32_e32 v190, 0x3a000000, v190
	v_add_f32_e32 v190, 0x358637bd, v190
	v_mul_f32_e32 v191, 0x3a000000, v191
	v_add_f32_e32 v191, 0x358637bd, v191
	v_mul_f32_e32 v192, 0x3a000000, v192
	v_add_f32_e32 v192, 0x358637bd, v192
	v_mul_f32_e32 v194, 0x3a000000, v194
	v_add_f32_e32 v194, 0x358637bd, v194
	v_mul_f32_e32 v195, 0x3a000000, v195
	v_add_f32_e32 v195, 0x358637bd, v195
	v_mul_f32_e32 v196, 0x3a000000, v196
	v_add_f32_e32 v196, 0x358637bd, v196
	v_mul_f32_e32 v198, 0x3a000000, v198
	v_add_f32_e32 v198, 0x358637bd, v198
	v_mul_f32_e32 v248, 0x3a000000, v248
	v_add_f32_e32 v248, 0x358637bd, v248
	v_rsq_f32_e32 v190, v190
	v_rsq_f32_e32 v191, v191
	v_rsq_f32_e32 v192, v192
	v_rsq_f32_e32 v194, v194
	v_rsq_f32_e32 v195, v195
	v_rsq_f32_e32 v196, v196
	v_rsq_f32_e32 v198, v198
	v_rsq_f32_e32 v248, v248
	s_mov_b32 s89, 1
.Lrs_mul:
	v_mul_f32_e32 v124, v124, v190
	v_mul_f32_e32 v125, v125, v190
	v_mul_f32_e32 v126, v126, v190
	v_mul_f32_e32 v127, v127, v190
	v_mul_f32_e32 v120, v120, v190
	v_mul_f32_e32 v121, v121, v190
	v_mul_f32_e32 v122, v122, v190
	v_mul_f32_e32 v123, v123, v190
	v_mul_f32_e32 v112, v112, v190
	v_mul_f32_e32 v113, v113, v190
	v_mul_f32_e32 v114, v114, v190
	v_mul_f32_e32 v115, v115, v190
	v_mul_f32_e32 v104, v104, v190
	v_mul_f32_e32 v105, v105, v190
	v_mul_f32_e32 v106, v106, v190
	v_mul_f32_e32 v107, v107, v190
	v_mul_f32_e32 v116, v116, v191
	v_mul_f32_e32 v117, v117, v191
	v_mul_f32_e32 v118, v118, v191
	v_mul_f32_e32 v119, v119, v191
	v_mul_f32_e32 v108, v108, v191
	v_mul_f32_e32 v109, v109, v191
	v_mul_f32_e32 v110, v110, v191
	v_mul_f32_e32 v111, v111, v191
	v_mul_f32_e32 v96, v96, v191
	v_mul_f32_e32 v97, v97, v191
	v_mul_f32_e32 v98, v98, v191
	v_mul_f32_e32 v99, v99, v191
	v_mul_f32_e32 v88, v88, v191
	v_mul_f32_e32 v89, v89, v191
	v_mul_f32_e32 v90, v90, v191
	v_mul_f32_e32 v91, v91, v191
	v_mul_f32_e32 v100, v100, v192
	v_mul_f32_e32 v101, v101, v192
	v_mul_f32_e32 v102, v102, v192
	v_mul_f32_e32 v103, v103, v192
	v_mul_f32_e32 v92, v92, v192
	v_mul_f32_e32 v93, v93, v192
	v_mul_f32_e32 v94, v94, v192
	v_mul_f32_e32 v95, v95, v192
	v_mul_f32_e32 v80, v80, v192
	v_mul_f32_e32 v81, v81, v192
	v_mul_f32_e32 v82, v82, v192
	v_mul_f32_e32 v83, v83, v192
	v_mul_f32_e32 v72, v72, v192
	v_mul_f32_e32 v73, v73, v192
	v_mul_f32_e32 v74, v74, v192
	v_mul_f32_e32 v75, v75, v192
	v_mul_f32_e32 v84, v84, v194
	v_mul_f32_e32 v85, v85, v194
	v_mul_f32_e32 v86, v86, v194
	v_mul_f32_e32 v87, v87, v194
	v_mul_f32_e32 v76, v76, v194
	v_mul_f32_e32 v77, v77, v194
	v_mul_f32_e32 v78, v78, v194
	v_mul_f32_e32 v79, v79, v194
	v_mul_f32_e32 v68, v68, v194
	v_mul_f32_e32 v69, v69, v194
	v_mul_f32_e32 v70, v70, v194
	v_mul_f32_e32 v71, v71, v194
	v_mul_f32_e32 v64, v64, v194
	v_mul_f32_e32 v65, v65, v194
	v_mul_f32_e32 v66, v66, v194
	v_mul_f32_e32 v67, v67, v194
	v_mul_f32_e32 v60, v60, v195
	v_mul_f32_e32 v61, v61, v195
	v_mul_f32_e32 v62, v62, v195
	v_mul_f32_e32 v63, v63, v195
	v_mul_f32_e32 v56, v56, v195
	v_mul_f32_e32 v57, v57, v195
	v_mul_f32_e32 v58, v58, v195
	v_mul_f32_e32 v59, v59, v195
	v_mul_f32_e32 v48, v48, v195
	v_mul_f32_e32 v49, v49, v195
	v_mul_f32_e32 v50, v50, v195
	v_mul_f32_e32 v51, v51, v195
	v_mul_f32_e32 v40, v40, v195
	v_mul_f32_e32 v41, v41, v195
	v_mul_f32_e32 v42, v42, v195
	v_mul_f32_e32 v43, v43, v195
	v_mul_f32_e32 v52, v52, v196
	v_mul_f32_e32 v53, v53, v196
	v_mul_f32_e32 v54, v54, v196
	v_mul_f32_e32 v55, v55, v196
	v_mul_f32_e32 v44, v44, v196
	v_mul_f32_e32 v45, v45, v196
	v_mul_f32_e32 v46, v46, v196
	v_mul_f32_e32 v47, v47, v196
	v_mul_f32_e32 v32, v32, v196
	v_mul_f32_e32 v33, v33, v196
	v_mul_f32_e32 v34, v34, v196
	v_mul_f32_e32 v35, v35, v196
	v_mul_f32_e32 v24, v24, v196
	v_mul_f32_e32 v25, v25, v196
	v_mul_f32_e32 v26, v26, v196
	v_mul_f32_e32 v27, v27, v196
	v_mul_f32_e32 v36, v36, v198
	v_mul_f32_e32 v37, v37, v198
	v_mul_f32_e32 v38, v38, v198
	v_mul_f32_e32 v39, v39, v198
	v_mul_f32_e32 v28, v28, v198
	v_mul_f32_e32 v29, v29, v198
	v_mul_f32_e32 v30, v30, v198
	v_mul_f32_e32 v31, v31, v198
	v_mul_f32_e32 v16, v16, v198
	v_mul_f32_e32 v17, v17, v198
	v_mul_f32_e32 v18, v18, v198
	v_mul_f32_e32 v19, v19, v198
	v_mul_f32_e32 v8, v8, v198
	v_mul_f32_e32 v9, v9, v198
	v_mul_f32_e32 v10, v10, v198
	v_mul_f32_e32 v11, v11, v198
	v_mul_f32_e32 v20, v20, v248
	v_mul_f32_e32 v21, v21, v248
	v_mul_f32_e32 v22, v22, v248
	v_mul_f32_e32 v23, v23, v248
	v_mul_f32_e32 v12, v12, v248
	v_mul_f32_e32 v13, v13, v248
	v_mul_f32_e32 v14, v14, v248
	v_mul_f32_e32 v15, v15, v248
	v_mul_f32_e32 v4, v4, v248
	v_mul_f32_e32 v5, v5, v248
	v_mul_f32_e32 v6, v6, v248
	v_mul_f32_e32 v7, v7, v248
	v_mul_f32_e32 v0, v0, v248
	v_mul_f32_e32 v1, v1, v248
	v_mul_f32_e32 v2, v2, v248
	v_mul_f32_e32 v3, v3, v248
